# last unit of each GEMM phase (SwiGLU/Scale no-next epilogue copy) stores write-through sc1: L2 mostly clean at the grid barrier release
# speedup vs baseline: 1.0074x; 1.0074x over previous
; __device__ __forceinline__ unsigned cvt_pk_bf16(float lo, float hi) { unsigned r; asm volatile("v_cvt_pk_bf16_f32 %0, %1, %2" : "=v"(r) : "v"(lo), "v"(hi)); return r; }
;     __device__ __forceinline__ void operator()(Acc& acc, const Unit& u, int wr, int wc, int fr, int fq, LAS unsigned char*, const LAS float* rst) const {
;     ...
;             for (int m = 0; m < 4; ++m) {
;                 const int row = row0 + ai * 128 + m * 16; const float rs = rsv[ai][m];
; #pragma unroll
;                 for (int bj = 0; bj < 2; ++bj) { const f32x4 v0 = acc[ai][bj][m][0] * rs, v1 = acc[ai][bj][m][1] * rs;
;                     u32x4 w; w.x = cvt_pk_bf16(v0[0], v0[1]); w.y = cvt_pk_bf16(v0[2], v0[3]); w.z = cvt_pk_bf16(v1[0], v1[1]); w.w = cvt_pk_bf16(v1[2], v1[3]);
;                     *(u32x4*)(O + (size_t)row * ldc + col0 + bj * 128) = w; }
.LBB0_644:
	v_lshl_add_u32 v131, s52, 8, v179
	v_ashrrev_i32_e32 v133, 31, v131
	v_pk_mul_f32 v[150:151], v[128:129], v[146:147] op_sel_hi:[1,0]
	v_pk_mul_f32 v[148:149], v[126:127], v[146:147] op_sel_hi:[1,0]
	v_pk_mul_f32 v[152:153], v[124:125], v[146:147] op_sel_hi:[1,0]
	v_lshl_or_b32 v134, s42, 8, v183
	v_pk_mul_f32 v[154:155], v[122:123], v[146:147] op_sel_hi:[1,0]
	v_cvt_pk_bf16_f32 v148, v148, v149
	v_cvt_pk_bf16_f32 v149, v150, v151
	v_mul_lo_u32 v133, v133, s56
	v_cvt_pk_bf16_f32 v150, v154, v155
	v_cvt_pk_bf16_f32 v151, v152, v153
	v_mad_u64_u32 v[152:153], s[0:1], v131, s56, 0
	v_ashrrev_i32_e32 v135, 31, v134
	v_add_u32_e32 v153, v153, v133
	v_lshl_add_u64 v[152:153], v[152:153], 1, s[34:35]
	v_lshlrev_b64 v[134:135], 1, v[134:135]
	v_lshl_add_u64 v[152:153], v[152:153], 0, v[134:135]
	flat_store_dwordx4 v[152:153], v[148:151] sc1
	v_pk_mul_f32 v[154:155], v[112:113], v[146:147] op_sel_hi:[1,0]
	v_pk_mul_f32 v[156:157], v[110:111], v[146:147] op_sel_hi:[1,0]
	v_pk_mul_f32 v[148:149], v[120:121], v[146:147] op_sel_hi:[1,0]
	v_pk_mul_f32 v[150:151], v[118:119], v[146:147] op_sel_hi:[1,0]
	v_or_b32_e32 v137, 16, v131
	v_cvt_pk_bf16_f32 v146, v150, v151
	v_cvt_pk_bf16_f32 v147, v148, v149
	v_cvt_pk_bf16_f32 v148, v156, v157
	v_cvt_pk_bf16_f32 v149, v154, v155
	flat_store_dwordx4 v[152:153], v[146:149] offset:256 sc1
	v_pk_mul_f32 v[150:151], v[108:109], v[144:145] op_sel_hi:[1,0]
	v_pk_mul_f32 v[152:153], v[106:107], v[144:145] op_sel_hi:[1,0]
	v_pk_mul_f32 v[148:149], v[116:117], v[144:145] op_sel_hi:[1,0]
	v_pk_mul_f32 v[146:147], v[114:115], v[144:145] op_sel_hi:[1,0]
	v_pk_mul_f32 v[154:155], v[94:95], v[144:145] op_sel_hi:[1,0]
	v_cvt_pk_bf16_f32 v146, v146, v147
	v_cvt_pk_bf16_f32 v147, v148, v149
	v_cvt_pk_bf16_f32 v148, v152, v153
	v_cvt_pk_bf16_f32 v149, v150, v151
	v_mad_u64_u32 v[150:151], s[0:1], v137, s56, 0
	v_add_u32_e32 v151, v151, v133
	v_lshl_add_u64 v[150:151], v[150:151], 1, s[34:35]
	v_lshl_add_u64 v[150:151], v[150:151], 0, v[134:135]
	flat_store_dwordx4 v[150:151], v[146:149] sc1
	v_pk_mul_f32 v[152:153], v[96:97], v[144:145] op_sel_hi:[1,0]
	v_or_b32_e32 v137, 32, v131
	v_pk_mul_f32 v[146:147], v[104:105], v[144:145] op_sel_hi:[1,0]
	v_pk_mul_f32 v[148:149], v[102:103], v[144:145] op_sel_hi:[1,0]
	s_nop 0
	v_cvt_pk_bf16_f32 v144, v148, v149
	v_cvt_pk_bf16_f32 v145, v146, v147
	v_cvt_pk_bf16_f32 v146, v154, v155
	v_cvt_pk_bf16_f32 v147, v152, v153
	flat_store_dwordx4 v[150:151], v[144:147] offset:256 sc1
	v_pk_mul_f32 v[148:149], v[92:93], v[142:143] op_sel_hi:[1,0]
	v_pk_mul_f32 v[150:151], v[90:91], v[142:143] op_sel_hi:[1,0]
	v_pk_mul_f32 v[146:147], v[100:101], v[142:143] op_sel_hi:[1,0]
	v_pk_mul_f32 v[144:145], v[98:99], v[142:143] op_sel_hi:[1,0]
	v_pk_mul_f32 v[152:153], v[78:79], v[142:143] op_sel_hi:[1,0]
	v_cvt_pk_bf16_f32 v144, v144, v145
	v_cvt_pk_bf16_f32 v145, v146, v147
	v_cvt_pk_bf16_f32 v146, v150, v151
	v_cvt_pk_bf16_f32 v147, v148, v149
	v_mad_u64_u32 v[148:149], s[0:1], v137, s56, 0
	v_add_u32_e32 v149, v149, v133
	v_lshl_add_u64 v[148:149], v[148:149], 1, s[34:35]
	v_lshl_add_u64 v[148:149], v[148:149], 0, v[134:135]
	flat_store_dwordx4 v[148:149], v[144:147] sc1
	v_pk_mul_f32 v[150:151], v[80:81], v[142:143] op_sel_hi:[1,0]
	v_or_b32_e32 v137, 48, v131
	v_pk_mul_f32 v[144:145], v[88:89], v[142:143] op_sel_hi:[1,0]
	v_pk_mul_f32 v[146:147], v[86:87], v[142:143] op_sel_hi:[1,0]
	s_nop 0
	v_cvt_pk_bf16_f32 v142, v146, v147
	v_cvt_pk_bf16_f32 v143, v144, v145
	v_cvt_pk_bf16_f32 v144, v152, v153
	v_cvt_pk_bf16_f32 v145, v150, v151
	flat_store_dwordx4 v[148:149], v[142:145] offset:256 sc1
	v_pk_mul_f32 v[146:147], v[76:77], v[140:141] op_sel_hi:[1,0]
	v_pk_mul_f32 v[148:149], v[74:75], v[140:141] op_sel_hi:[1,0]
	v_pk_mul_f32 v[144:145], v[84:85], v[140:141] op_sel_hi:[1,0]
	v_pk_mul_f32 v[142:143], v[82:83], v[140:141] op_sel_hi:[1,0]
	v_pk_mul_f32 v[150:151], v[66:67], v[140:141] op_sel_hi:[1,0]
	v_cvt_pk_bf16_f32 v142, v142, v143
	v_cvt_pk_bf16_f32 v143, v144, v145
	v_cvt_pk_bf16_f32 v144, v148, v149
	v_cvt_pk_bf16_f32 v145, v146, v147
	v_mad_u64_u32 v[146:147], s[0:1], v137, s56, 0
	v_add_u32_e32 v147, v147, v133
	v_lshl_add_u64 v[146:147], v[146:147], 1, s[34:35]
	v_lshl_add_u64 v[146:147], v[146:147], 0, v[134:135]
	flat_store_dwordx4 v[146:147], v[142:145] sc1
	v_pk_mul_f32 v[148:149], v[68:69], v[140:141] op_sel_hi:[1,0]
	v_add_u32_e32 v133, 0x80, v131
	v_pk_mul_f32 v[142:143], v[72:73], v[140:141] op_sel_hi:[1,0]
	v_pk_mul_f32 v[144:145], v[70:71], v[140:141] op_sel_hi:[1,0]
	v_ashrrev_i32_e32 v137, 31, v133
	v_cvt_pk_bf16_f32 v140, v144, v145
	v_cvt_pk_bf16_f32 v141, v142, v143
	v_cvt_pk_bf16_f32 v142, v150, v151
	v_cvt_pk_bf16_f32 v143, v148, v149
	flat_store_dwordx4 v[146:147], v[140:143] offset:256 sc1
	v_pk_mul_f32 v[144:145], v[60:61], v[138:139] op_sel_hi:[1,0]
; __device__ __forceinline__ unsigned cvt_pk_bf16(float lo, float hi) { unsigned r; asm volatile("v_cvt_pk_bf16_f32 %0, %1, %2" : "=v"(r) : "v"(lo), "v"(hi)); return r; }
;     __device__ __forceinline__ void operator()(Acc& acc, const Unit& u, int wr, int wc, int fr, int fq, LAS unsigned char*, const LAS float* rst) const {
;     ...
;             for (int m = 0; m < 4; ++m) {
;                 const int row = row0 + ai * 128 + m * 16; const float rs = rsv[ai][m];
; #pragma unroll
;                 for (int bj = 0; bj < 2; ++bj) { const f32x4 v0 = acc[ai][bj][m][0] * rs, v1 = acc[ai][bj][m][1] * rs;
;                     u32x4 w; w.x = cvt_pk_bf16(v0[0], v0[1]); w.y = cvt_pk_bf16(v0[2], v0[3]); w.z = cvt_pk_bf16(v1[0], v1[1]); w.w = cvt_pk_bf16(v1[2], v1[3]);
;                     *(u32x4*)(O + (size_t)row * ldc + col0 + bj * 128) = w; }
	v_pk_mul_f32 v[146:147], v[58:59], v[138:139] op_sel_hi:[1,0]
	v_pk_mul_f32 v[142:143], v[64:65], v[138:139] op_sel_hi:[1,0]
	v_pk_mul_f32 v[140:141], v[62:63], v[138:139] op_sel_hi:[1,0]
	v_pk_mul_f32 v[148:149], v[46:47], v[138:139] op_sel_hi:[1,0]
	v_cvt_pk_bf16_f32 v140, v140, v141
	v_cvt_pk_bf16_f32 v141, v142, v143
	v_cvt_pk_bf16_f32 v142, v146, v147
	v_cvt_pk_bf16_f32 v143, v144, v145
	v_mad_u64_u32 v[144:145], s[0:1], v133, s56, 0
	v_mov_b32_e32 v146, v145
	v_mad_u64_u32 v[146:147], s[0:1], v137, s56, v[146:147]
	v_mov_b32_e32 v145, v146
	v_lshl_add_u64 v[144:145], v[144:145], 1, s[34:35]
	v_lshl_add_u64 v[144:145], v[144:145], 0, v[134:135]
	flat_store_dwordx4 v[144:145], v[140:143] sc1
	v_add_u32_e32 v133, 0x90, v131
	v_pk_mul_f32 v[146:147], v[48:49], v[138:139] op_sel_hi:[1,0]
	v_pk_mul_f32 v[140:141], v[56:57], v[138:139] op_sel_hi:[1,0]
	v_pk_mul_f32 v[142:143], v[54:55], v[138:139] op_sel_hi:[1,0]
	v_ashrrev_i32_e32 v137, 31, v133
	v_cvt_pk_bf16_f32 v138, v142, v143
	v_cvt_pk_bf16_f32 v139, v140, v141
	v_cvt_pk_bf16_f32 v140, v148, v149
	v_cvt_pk_bf16_f32 v141, v146, v147
	flat_store_dwordx4 v[144:145], v[138:141] offset:256 sc1
	v_pk_mul_f32 v[142:143], v[44:45], v[136:137] op_sel_hi:[1,0]
	v_pk_mul_f32 v[144:145], v[42:43], v[136:137] op_sel_hi:[1,0]
	v_pk_mul_f32 v[140:141], v[52:53], v[136:137] op_sel_hi:[1,0]
	v_pk_mul_f32 v[138:139], v[50:51], v[136:137] op_sel_hi:[1,0]
	v_pk_mul_f32 v[146:147], v[30:31], v[136:137] op_sel_hi:[1,0]
	v_cvt_pk_bf16_f32 v138, v138, v139
	v_cvt_pk_bf16_f32 v139, v140, v141
	v_cvt_pk_bf16_f32 v140, v144, v145
	v_cvt_pk_bf16_f32 v141, v142, v143
	v_mad_u64_u32 v[142:143], s[0:1], v133, s56, 0
	v_mov_b32_e32 v144, v143
	v_mad_u64_u32 v[144:145], s[0:1], v137, s56, v[144:145]
	v_mov_b32_e32 v143, v144
	v_lshl_add_u64 v[142:143], v[142:143], 1, s[34:35]
	v_lshl_add_u64 v[142:143], v[142:143], 0, v[134:135]
	flat_store_dwordx4 v[142:143], v[138:141] sc1
	v_pk_mul_f32 v[144:145], v[32:33], v[136:137] op_sel_hi:[1,0]
	v_add_u32_e32 v133, 0xa0, v131
	v_pk_mul_f32 v[138:139], v[40:41], v[136:137] op_sel_hi:[1,0]
	v_pk_mul_f32 v[140:141], v[38:39], v[136:137] op_sel_hi:[1,0]
	v_add_u32_e32 v131, 0xb0, v131
	v_cvt_pk_bf16_f32 v136, v140, v141
	v_cvt_pk_bf16_f32 v137, v138, v139
	v_cvt_pk_bf16_f32 v138, v146, v147
	v_cvt_pk_bf16_f32 v139, v144, v145
	flat_store_dwordx4 v[142:143], v[136:139] offset:256 sc1
	v_pk_mul_f32 v[140:141], v[28:29], v[132:133] op_sel_hi:[1,0]
	v_pk_mul_f32 v[142:143], v[26:27], v[132:133] op_sel_hi:[1,0]
	v_pk_mul_f32 v[138:139], v[36:37], v[132:133] op_sel_hi:[1,0]
	v_pk_mul_f32 v[136:137], v[34:35], v[132:133] op_sel_hi:[1,0]
	v_ashrrev_i32_e32 v144, 31, v133
	v_cvt_pk_bf16_f32 v136, v136, v137
	v_cvt_pk_bf16_f32 v137, v138, v139
	v_cvt_pk_bf16_f32 v138, v142, v143
	v_cvt_pk_bf16_f32 v139, v140, v141
	v_mad_u64_u32 v[140:141], s[0:1], v133, s56, 0
	v_mov_b32_e32 v142, v141
	v_mad_u64_u32 v[142:143], s[0:1], v144, s56, v[142:143]
	v_mov_b32_e32 v141, v142
	v_lshl_add_u64 v[140:141], v[140:141], 1, s[34:35]
	v_lshl_add_u64 v[140:141], v[140:141], 0, v[134:135]
	flat_store_dwordx4 v[140:141], v[136:139] sc1
	v_pk_mul_f32 v[142:143], v[16:17], v[132:133] op_sel_hi:[1,0]
	s_nop 0
	v_pk_mul_f32 v[136:137], v[22:23], v[132:133] op_sel_hi:[1,0]
	v_pk_mul_f32 v[138:139], v[24:25], v[132:133] op_sel_hi:[1,0]
	v_pk_mul_f32 v[132:133], v[14:15], v[132:133] op_sel_hi:[1,0]
	v_cvt_pk_bf16_f32 v136, v136, v137
	v_cvt_pk_bf16_f32 v137, v138, v139
	s_nop 0
	v_cvt_pk_bf16_f32 v138, v132, v133
	v_cvt_pk_bf16_f32 v139, v142, v143
	flat_store_dwordx4 v[140:141], v[136:139] offset:256 sc1
	v_pk_mul_f32 v[132:133], v[20:21], v[130:131] op_sel_hi:[1,0]
	v_pk_mul_f32 v[140:141], v[12:13], v[130:131] op_sel_hi:[1,0]
	v_pk_mul_f32 v[136:137], v[18:19], v[130:131] op_sel_hi:[1,0]
	v_pk_mul_f32 v[138:139], v[10:11], v[130:131] op_sel_hi:[1,0]
	v_cvt_pk_bf16_f32 v136, v136, v137
	v_cvt_pk_bf16_f32 v137, v132, v133
	v_mad_u64_u32 v[132:133], s[0:1], v131, s56, 0
	v_ashrrev_i32_e32 v142, 31, v131
	v_cvt_pk_bf16_f32 v138, v138, v139
	v_cvt_pk_bf16_f32 v139, v140, v141
	v_mov_b32_e32 v140, v133
	v_mad_u64_u32 v[140:141], s[0:1], v142, s56, v[140:141]
	v_mov_b32_e32 v133, v140
	v_lshl_add_u64 v[132:133], v[132:133], 1, s[34:35]
	v_lshl_add_u64 v[134:135], v[132:133], 0, v[134:135]
	v_pk_mul_f32 v[132:133], v[8:9], v[130:131] op_sel_hi:[1,0]
	flat_store_dwordx4 v[134:135], v[136:139] sc1
	v_pk_mul_f32 v[140:141], v[2:3], v[130:131] op_sel_hi:[1,0]
	s_nop 0
	v_pk_mul_f32 v[136:137], v[6:7], v[130:131] op_sel_hi:[1,0]
	v_pk_mul_f32 v[138:139], v[4:5], v[130:131] op_sel_hi:[1,0]
	v_cvt_pk_bf16_f32 v130, v136, v137
	v_cvt_pk_bf16_f32 v131, v132, v133
	v_cvt_pk_bf16_f32 v132, v140, v141
	s_nop 0
	v_cvt_pk_bf16_f32 v133, v138, v139
	flat_store_dwordx4 v[134:135], v[130:133] offset:256 sc1

; __device__ __forceinline__ unsigned cvt_pk_bf16(float lo, float hi) { unsigned r; asm volatile("v_cvt_pk_bf16_f32 %0, %1, %2" : "=v"(r) : "v"(lo), "v"(hi)); return r; }
;     __device__ __forceinline__ void operator()(Acc& acc, const Unit& u, int wr, int wc, int fr, int fq, LAS unsigned char*, const LAS float* rst) const {
;     ...
;             for (int m = 0; m < 4; ++m) {
;                 const int row = row0 + ai * 128 + m * 16; const float rs = rsv[ai][m];
;                 const float cexp = -1.4426950408889634f * rs, rs2 = rs * rs;
;                 unsigned w[4];
; #pragma unroll
;                 for (int n = 0; n < 2; ++n)
; #pragma unroll
;                     for (int p = 0; p < 2; ++p) { const f32x2 g2 = {acc[ai][0][m][n][2 * p], acc[ai][0][m][n][2 * p + 1]}, u2 = {acc[ai][1][m][n][2 * p], acc[ai][1][m][n][2 * p + 1]};
;                         f32x2 e2 = g2 * cexp; e2.x = __builtin_amdgcn_exp2f(e2.x); e2.y = __builtin_amdgcn_exp2f(e2.y);
;                         const f32x2 d2 = e2 + 1.0f; f32x2 r2; r2.x = __builtin_amdgcn_rcpf(d2.x); r2.y = __builtin_amdgcn_rcpf(d2.y);
;                         const f32x2 o2 = ((g2 * u2) * rs2) * r2; w[n * 2 + p] = cvt_pk_bf16(o2.x, o2.y); }
;                 *(u32x4*)(O + (size_t)row * FF + col0) = (u32x4){w[0], w[1], w[2], w[3]};
.LBB0_773:
	s_mov_b64 s[10:11], -1
	s_and_b64 vcc, exec, s[0:1]
	v_lshl_add_u32 v195, s58, 8, v182
	v_lshl_or_b32 v174, s59, 7, v193
	v_pk_mul_f32 v[122:123], v[126:127], v[122:123]
	v_pk_mul_f32 v[114:115], v[118:119], v[114:115]
	v_pk_mul_f32 v[106:107], v[110:111], v[106:107]
	v_pk_mul_f32 v[98:99], v[102:103], v[98:99]
	v_pk_mul_f32 v[90:91], v[94:95], v[90:91]
	v_pk_mul_f32 v[82:83], v[86:87], v[82:83]
	v_pk_mul_f32 v[74:75], v[78:79], v[74:75]
	v_pk_mul_f32 v[66:67], v[70:71], v[66:67]
	v_pk_mul_f32 v[58:59], v[62:63], v[58:59]
	v_pk_mul_f32 v[50:51], v[54:55], v[50:51]
	v_pk_mul_f32 v[42:43], v[46:47], v[42:43]
	v_pk_mul_f32 v[34:35], v[38:39], v[34:35]
	v_pk_mul_f32 v[26:27], v[30:31], v[26:27]
	v_pk_mul_f32 v[18:19], v[22:23], v[18:19]
	s_cbranch_vccz .LBB0_776
	ds_read2_b32 v[144:145], v191 offset1:16
	ds_read2_b32 v[136:137], v191 offset0:64 offset1:80
	ds_read2_b32 v[138:139], v191 offset0:32 offset1:48
	ds_read2_b32 v[130:131], v191 offset0:96 offset1:112
	v_pk_mul_f32 v[142:143], v[128:129], v[124:125]
	s_waitcnt lgkmcnt(0)
	v_mul_f32_e32 v132, 0xbfb8aa3b, v144
	v_pk_mul_f32 v[140:141], v[126:127], v[132:133] op_sel_hi:[1,0]
	v_mul_f32_e32 v134, v144, v144
	v_exp_f32_e32 v140, v140
	v_exp_f32_e32 v141, v141
	v_pk_mul_f32 v[146:147], v[122:123], v[134:135] op_sel_hi:[1,0]
	v_pk_mul_f32 v[142:143], v[142:143], v[134:135] op_sel_hi:[1,0]
	v_pk_mul_f32 v[148:149], v[114:115], v[134:135] op_sel_hi:[1,0]
	v_pk_add_f32 v[140:141], v[140:141], 1.0 op_sel_hi:[1,0]
	v_ashrrev_i32_e32 v175, 31, v174
	v_rcp_f32_e32 v140, v140
	v_rcp_f32_e32 v141, v141
	v_mul_f32_e32 v144, 0xbfb8aa3b, v145
	v_pk_mul_f32 v[140:141], v[146:147], v[140:141]
	v_pk_mul_f32 v[146:147], v[128:129], v[132:133] op_sel_hi:[1,0]
	v_cvt_pk_bf16_f32 v140, v140, v141
	s_nop 0
	v_exp_f32_e32 v146, v146
	v_exp_f32_e32 v147, v147
	s_nop 0
	v_pk_add_f32 v[146:147], v[146:147], 1.0 op_sel_hi:[1,0]
	s_nop 0
	v_rcp_f32_e32 v146, v146
	v_rcp_f32_e32 v147, v147
	s_nop 0
	v_pk_mul_f32 v[142:143], v[142:143], v[146:147]
	s_nop 0
	v_cvt_pk_bf16_f32 v141, v142, v143
	v_pk_mul_f32 v[142:143], v[118:119], v[132:133] op_sel_hi:[1,0]
	v_pk_mul_f32 v[132:133], v[120:121], v[132:133] op_sel_hi:[1,0]
	v_exp_f32_e32 v142, v142
	v_exp_f32_e32 v143, v143
	v_exp_f32_e32 v132, v132
	v_exp_f32_e32 v133, v133
	v_pk_mul_f32 v[146:147], v[120:121], v[116:117]
	v_pk_add_f32 v[142:143], v[142:143], 1.0 op_sel_hi:[1,0]
	v_pk_mul_f32 v[134:135], v[146:147], v[134:135] op_sel_hi:[1,0]
	v_pk_add_f32 v[132:133], v[132:133], 1.0 op_sel_hi:[1,0]
	v_rcp_f32_e32 v142, v142
	v_rcp_f32_e32 v143, v143
	v_rcp_f32_e32 v132, v132
	v_rcp_f32_e32 v133, v133
	v_pk_mul_f32 v[142:143], v[148:149], v[142:143]
	s_nop 0
	v_cvt_pk_bf16_f32 v142, v142, v143
	v_pk_mul_f32 v[132:133], v[134:135], v[132:133]
	v_lshlrev_b64 v[134:135], 1, v[174:175]
	v_cvt_pk_bf16_f32 v143, v132, v133
	v_mov_b64_e32 v[132:133], s[16:17]
	v_mad_i64_i32 v[146:147], s[0:1], v195, s80, v[132:133]
	v_lshl_add_u64 v[146:147], v[146:147], 0, v[134:135]
	flat_store_dwordx4 v[146:147], v[140:143] sc1
	v_mul_f32_e32 v146, v145, v145
	v_pk_mul_f32 v[148:149], v[106:107], v[146:147] op_sel_hi:[1,0]
	v_pk_mul_f32 v[140:141], v[110:111], v[144:145] op_sel_hi:[1,0]
	v_pk_mul_f32 v[142:143], v[112:113], v[108:109]
	v_exp_f32_e32 v140, v140
	v_exp_f32_e32 v141, v141
	v_pk_mul_f32 v[142:143], v[142:143], v[146:147] op_sel_hi:[1,0]
	v_pk_mul_f32 v[150:151], v[98:99], v[146:147] op_sel_hi:[1,0]
	v_pk_add_f32 v[140:141], v[140:141], 1.0 op_sel_hi:[1,0]
	s_nop 0
	v_rcp_f32_e32 v140, v140
	v_rcp_f32_e32 v141, v141
	s_nop 0
	v_pk_mul_f32 v[140:141], v[148:149], v[140:141]
	v_pk_mul_f32 v[148:149], v[112:113], v[144:145] op_sel_hi:[1,0]
	v_cvt_pk_bf16_f32 v140, v140, v141
	s_nop 0
	v_exp_f32_e32 v148, v148
	v_exp_f32_e32 v149, v149
	s_nop 0
	v_pk_add_f32 v[148:149], v[148:149], 1.0 op_sel_hi:[1,0]
	s_nop 0
	v_rcp_f32_e32 v148, v148
	v_rcp_f32_e32 v149, v149
	s_nop 0
	v_pk_mul_f32 v[142:143], v[142:143], v[148:149]
	s_nop 0
	v_cvt_pk_bf16_f32 v141, v142, v143
	v_pk_mul_f32 v[142:143], v[102:103], v[144:145] op_sel_hi:[1,0]
	v_pk_mul_f32 v[144:145], v[104:105], v[144:145] op_sel_hi:[1,0]
	v_exp_f32_e32 v142, v142
	v_exp_f32_e32 v143, v143
	v_exp_f32_e32 v144, v144
	v_exp_f32_e32 v145, v145
	v_pk_mul_f32 v[148:149], v[104:105], v[100:101]
	v_pk_add_f32 v[142:143], v[142:143], 1.0 op_sel_hi:[1,0]
	v_pk_mul_f32 v[146:147], v[148:149], v[146:147] op_sel_hi:[1,0]
	v_pk_add_f32 v[144:145], v[144:145], 1.0 op_sel_hi:[1,0]
	v_rcp_f32_e32 v142, v142
	v_rcp_f32_e32 v143, v143
	v_rcp_f32_e32 v144, v144
	v_rcp_f32_e32 v145, v145
	v_pk_mul_f32 v[142:143], v[150:151], v[142:143]
	s_nop 0
	v_cvt_pk_bf16_f32 v142, v142, v143
	v_pk_mul_f32 v[144:145], v[146:147], v[144:145]
	s_nop 0
	v_cvt_pk_bf16_f32 v143, v144, v145
	v_or_b32_e32 v144, 16, v195
	v_mad_i64_i32 v[144:145], s[0:1], v144, s80, v[132:133]
	v_lshl_add_u64 v[144:145], v[144:145], 0, v[134:135]
	flat_store_dwordx4 v[144:145], v[140:143] sc1
	v_mul_f32_e32 v144, 0xbfb8aa3b, v138
	v_mul_f32_e32 v138, v138, v138
	v_pk_mul_f32 v[140:141], v[94:95], v[144:145] op_sel_hi:[1,0]
	v_pk_mul_f32 v[146:147], v[90:91], v[138:139] op_sel_hi:[1,0]
	v_exp_f32_e32 v140, v140
	v_exp_f32_e32 v141, v141
	v_pk_mul_f32 v[142:143], v[96:97], v[92:93]
	v_pk_mul_f32 v[148:149], v[82:83], v[138:139] op_sel_hi:[1,0]
	v_pk_mul_f32 v[142:143], v[142:143], v[138:139] op_sel_hi:[1,0]
	v_pk_add_f32 v[140:141], v[140:141], 1.0 op_sel_hi:[1,0]
	s_nop 0
	v_rcp_f32_e32 v140, v140
	v_rcp_f32_e32 v141, v141
	s_nop 0
	v_pk_mul_f32 v[140:141], v[146:147], v[140:141]
	v_pk_mul_f32 v[146:147], v[96:97], v[144:145] op_sel_hi:[1,0]
	v_cvt_pk_bf16_f32 v140, v140, v141
; __device__ __forceinline__ unsigned cvt_pk_bf16(float lo, float hi) { unsigned r; asm volatile("v_cvt_pk_bf16_f32 %0, %1, %2" : "=v"(r) : "v"(lo), "v"(hi)); return r; }
;     __device__ __forceinline__ void operator()(Acc& acc, const Unit& u, int wr, int wc, int fr, int fq, LAS unsigned char*, const LAS float* rst) const {
;     ...
;             for (int m = 0; m < 4; ++m) {
;                 const int row = row0 + ai * 128 + m * 16; const float rs = rsv[ai][m];
;                 const float cexp = -1.4426950408889634f * rs, rs2 = rs * rs;
;                 unsigned w[4];
; #pragma unroll
;                 for (int n = 0; n < 2; ++n)
; #pragma unroll
;                     for (int p = 0; p < 2; ++p) { const f32x2 g2 = {acc[ai][0][m][n][2 * p], acc[ai][0][m][n][2 * p + 1]}, u2 = {acc[ai][1][m][n][2 * p], acc[ai][1][m][n][2 * p + 1]};
;                         f32x2 e2 = g2 * cexp; e2.x = __builtin_amdgcn_exp2f(e2.x); e2.y = __builtin_amdgcn_exp2f(e2.y);
;                         const f32x2 d2 = e2 + 1.0f; f32x2 r2; r2.x = __builtin_amdgcn_rcpf(d2.x); r2.y = __builtin_amdgcn_rcpf(d2.y);
;                         const f32x2 o2 = ((g2 * u2) * rs2) * r2; w[n * 2 + p] = cvt_pk_bf16(o2.x, o2.y); }
;                 *(u32x4*)(O + (size_t)row * FF + col0) = (u32x4){w[0], w[1], w[2], w[3]};
	s_nop 0
	v_exp_f32_e32 v146, v146
	v_exp_f32_e32 v147, v147
	s_nop 0
	v_pk_add_f32 v[146:147], v[146:147], 1.0 op_sel_hi:[1,0]
	s_nop 0
	v_rcp_f32_e32 v146, v146
	v_rcp_f32_e32 v147, v147
	s_nop 0
	v_pk_mul_f32 v[142:143], v[142:143], v[146:147]
	s_nop 0
	v_cvt_pk_bf16_f32 v141, v142, v143
	v_pk_mul_f32 v[142:143], v[86:87], v[144:145] op_sel_hi:[1,0]
	v_pk_mul_f32 v[144:145], v[88:89], v[144:145] op_sel_hi:[1,0]
	v_exp_f32_e32 v142, v142
	v_exp_f32_e32 v143, v143
	v_exp_f32_e32 v144, v144
	v_exp_f32_e32 v145, v145
	v_pk_mul_f32 v[146:147], v[88:89], v[84:85]
	v_pk_add_f32 v[142:143], v[142:143], 1.0 op_sel_hi:[1,0]
	v_pk_mul_f32 v[146:147], v[146:147], v[138:139] op_sel_hi:[1,0]
	v_pk_add_f32 v[144:145], v[144:145], 1.0 op_sel_hi:[1,0]
	v_rcp_f32_e32 v142, v142
	v_rcp_f32_e32 v143, v143
	v_rcp_f32_e32 v144, v144
	v_rcp_f32_e32 v145, v145
	v_or_b32_e32 v138, 32, v195
	v_pk_mul_f32 v[142:143], v[148:149], v[142:143]
	v_pk_mul_f32 v[144:145], v[146:147], v[144:145]
	v_cvt_pk_bf16_f32 v142, v142, v143
	s_nop 0
	v_cvt_pk_bf16_f32 v143, v144, v145
	v_mad_i64_i32 v[144:145], s[0:1], v138, s80, v[132:133]
	v_lshl_add_u64 v[144:145], v[144:145], 0, v[134:135]
	flat_store_dwordx4 v[144:145], v[140:143] sc1
	v_mul_f32_e32 v144, v139, v139
	v_pk_mul_f32 v[146:147], v[74:75], v[144:145] op_sel_hi:[1,0]
	v_mul_f32_e32 v142, 0xbfb8aa3b, v139
	v_pk_mul_f32 v[138:139], v[78:79], v[142:143] op_sel_hi:[1,0]
	v_pk_mul_f32 v[140:141], v[80:81], v[76:77]
	v_exp_f32_e32 v138, v138
	v_exp_f32_e32 v139, v139
	v_pk_mul_f32 v[140:141], v[140:141], v[144:145] op_sel_hi:[1,0]
	v_pk_mul_f32 v[148:149], v[66:67], v[144:145] op_sel_hi:[1,0]
	v_pk_add_f32 v[138:139], v[138:139], 1.0 op_sel_hi:[1,0]
	s_nop 0
	v_rcp_f32_e32 v138, v138
	v_rcp_f32_e32 v139, v139
	s_nop 0
	v_pk_mul_f32 v[138:139], v[146:147], v[138:139]
	v_pk_mul_f32 v[146:147], v[80:81], v[142:143] op_sel_hi:[1,0]
	v_cvt_pk_bf16_f32 v138, v138, v139
	s_nop 0
	v_exp_f32_e32 v146, v146
	v_exp_f32_e32 v147, v147
	s_nop 0
	v_pk_add_f32 v[146:147], v[146:147], 1.0 op_sel_hi:[1,0]
	s_nop 0
	v_rcp_f32_e32 v146, v146
	v_rcp_f32_e32 v147, v147
	s_nop 0
	v_pk_mul_f32 v[140:141], v[140:141], v[146:147]
	s_nop 0
	v_cvt_pk_bf16_f32 v139, v140, v141
	v_pk_mul_f32 v[140:141], v[70:71], v[142:143] op_sel_hi:[1,0]
	v_pk_mul_f32 v[142:143], v[72:73], v[142:143] op_sel_hi:[1,0]
	v_exp_f32_e32 v140, v140
	v_exp_f32_e32 v141, v141
	v_exp_f32_e32 v142, v142
	v_exp_f32_e32 v143, v143
	v_pk_mul_f32 v[146:147], v[72:73], v[68:69]
	v_pk_add_f32 v[140:141], v[140:141], 1.0 op_sel_hi:[1,0]
	v_pk_mul_f32 v[144:145], v[146:147], v[144:145] op_sel_hi:[1,0]
	v_pk_add_f32 v[142:143], v[142:143], 1.0 op_sel_hi:[1,0]
	v_rcp_f32_e32 v140, v140
	v_rcp_f32_e32 v141, v141
	v_rcp_f32_e32 v142, v142
	v_rcp_f32_e32 v143, v143
	v_pk_mul_f32 v[140:141], v[148:149], v[140:141]
	s_nop 0
	v_cvt_pk_bf16_f32 v140, v140, v141
	v_pk_mul_f32 v[142:143], v[144:145], v[142:143]
	v_add_u32_e32 v148, 0x80, v195
	v_cvt_pk_bf16_f32 v141, v142, v143
	v_or_b32_e32 v142, 48, v195
	v_mad_i64_i32 v[142:143], s[0:1], v142, s80, v[132:133]
	v_lshl_add_u64 v[142:143], v[142:143], 0, v[134:135]
	flat_store_dwordx4 v[142:143], v[138:141] sc1
	v_mul_f32_e32 v142, 0xbfb8aa3b, v136
	v_mul_f32_e32 v136, v136, v136
	v_pk_mul_f32 v[138:139], v[62:63], v[142:143] op_sel_hi:[1,0]
	v_pk_mul_f32 v[144:145], v[58:59], v[136:137] op_sel_hi:[1,0]
	v_exp_f32_e32 v138, v138
	v_exp_f32_e32 v139, v139
	v_pk_mul_f32 v[140:141], v[64:65], v[60:61]
	v_pk_mul_f32 v[146:147], v[50:51], v[136:137] op_sel_hi:[1,0]
	v_pk_mul_f32 v[140:141], v[140:141], v[136:137] op_sel_hi:[1,0]
	v_pk_add_f32 v[138:139], v[138:139], 1.0 op_sel_hi:[1,0]
	s_nop 0
	v_rcp_f32_e32 v138, v138
	v_rcp_f32_e32 v139, v139
	s_nop 0
	v_pk_mul_f32 v[138:139], v[144:145], v[138:139]
	v_pk_mul_f32 v[144:145], v[64:65], v[142:143] op_sel_hi:[1,0]
	v_cvt_pk_bf16_f32 v138, v138, v139
	s_nop 0
	v_exp_f32_e32 v144, v144
	v_exp_f32_e32 v145, v145
	s_nop 0
	v_pk_add_f32 v[144:145], v[144:145], 1.0 op_sel_hi:[1,0]
	s_nop 0
	v_rcp_f32_e32 v144, v144
	v_rcp_f32_e32 v145, v145
	s_nop 0
	v_pk_mul_f32 v[140:141], v[140:141], v[144:145]
	s_nop 0
	v_cvt_pk_bf16_f32 v139, v140, v141
	v_pk_mul_f32 v[140:141], v[54:55], v[142:143] op_sel_hi:[1,0]
	v_pk_mul_f32 v[142:143], v[56:57], v[142:143] op_sel_hi:[1,0]
	v_exp_f32_e32 v140, v140
	v_exp_f32_e32 v141, v141
	v_exp_f32_e32 v142, v142
	v_exp_f32_e32 v143, v143
	v_pk_mul_f32 v[144:145], v[56:57], v[52:53]
	v_pk_add_f32 v[140:141], v[140:141], 1.0 op_sel_hi:[1,0]
	v_pk_mul_f32 v[144:145], v[144:145], v[136:137] op_sel_hi:[1,0]
	v_pk_add_f32 v[142:143], v[142:143], 1.0 op_sel_hi:[1,0]
	v_rcp_f32_e32 v140, v140
	v_rcp_f32_e32 v141, v141
	v_rcp_f32_e32 v142, v142
	v_rcp_f32_e32 v143, v143
	v_pk_mul_f32 v[140:141], v[146:147], v[140:141]
	s_nop 0
	v_cvt_pk_bf16_f32 v140, v140, v141
	v_pk_mul_f32 v[142:143], v[144:145], v[142:143]
	s_nop 0
	v_cvt_pk_bf16_f32 v141, v142, v143
	v_mad_i64_i32 v[142:143], s[0:1], v148, s80, v[132:133]
	v_lshl_add_u64 v[142:143], v[142:143], 0, v[134:135]
	flat_store_dwordx4 v[142:143], v[138:141] sc1
	v_mul_f32_e32 v142, v137, v137
	v_pk_mul_f32 v[144:145], v[42:43], v[142:143] op_sel_hi:[1,0]
	v_mul_f32_e32 v140, 0xbfb8aa3b, v137
	v_pk_mul_f32 v[136:137], v[46:47], v[140:141] op_sel_hi:[1,0]
	v_pk_mul_f32 v[138:139], v[48:49], v[44:45]
	v_exp_f32_e32 v136, v136
	v_exp_f32_e32 v137, v137
	v_pk_mul_f32 v[138:139], v[138:139], v[142:143] op_sel_hi:[1,0]
	v_pk_mul_f32 v[146:147], v[34:35], v[142:143] op_sel_hi:[1,0]
; __device__ __forceinline__ unsigned cvt_pk_bf16(float lo, float hi) { unsigned r; asm volatile("v_cvt_pk_bf16_f32 %0, %1, %2" : "=v"(r) : "v"(lo), "v"(hi)); return r; }
;     __device__ __forceinline__ void operator()(Acc& acc, const Unit& u, int wr, int wc, int fr, int fq, LAS unsigned char*, const LAS float* rst) const {
;     ...
;             for (int m = 0; m < 4; ++m) {
;                 const int row = row0 + ai * 128 + m * 16; const float rs = rsv[ai][m];
;                 const float cexp = -1.4426950408889634f * rs, rs2 = rs * rs;
;                 unsigned w[4];
; #pragma unroll
;                 for (int n = 0; n < 2; ++n)
; #pragma unroll
;                     for (int p = 0; p < 2; ++p) { const f32x2 g2 = {acc[ai][0][m][n][2 * p], acc[ai][0][m][n][2 * p + 1]}, u2 = {acc[ai][1][m][n][2 * p], acc[ai][1][m][n][2 * p + 1]};
;                         f32x2 e2 = g2 * cexp; e2.x = __builtin_amdgcn_exp2f(e2.x); e2.y = __builtin_amdgcn_exp2f(e2.y);
;                         const f32x2 d2 = e2 + 1.0f; f32x2 r2; r2.x = __builtin_amdgcn_rcpf(d2.x); r2.y = __builtin_amdgcn_rcpf(d2.y);
;                         const f32x2 o2 = ((g2 * u2) * rs2) * r2; w[n * 2 + p] = cvt_pk_bf16(o2.x, o2.y); }
;                 *(u32x4*)(O + (size_t)row * FF + col0) = (u32x4){w[0], w[1], w[2], w[3]};
	v_pk_add_f32 v[136:137], v[136:137], 1.0 op_sel_hi:[1,0]
	s_nop 0
	v_rcp_f32_e32 v136, v136
	v_rcp_f32_e32 v137, v137
	s_nop 0
	v_pk_mul_f32 v[136:137], v[144:145], v[136:137]
	v_pk_mul_f32 v[144:145], v[48:49], v[140:141] op_sel_hi:[1,0]
	v_cvt_pk_bf16_f32 v136, v136, v137
	s_nop 0
	v_exp_f32_e32 v144, v144
	v_exp_f32_e32 v145, v145
	s_nop 0
	v_pk_add_f32 v[144:145], v[144:145], 1.0 op_sel_hi:[1,0]
	s_nop 0
	v_rcp_f32_e32 v144, v144
	v_rcp_f32_e32 v145, v145
	s_nop 0
	v_pk_mul_f32 v[138:139], v[138:139], v[144:145]
	s_nop 0
	v_cvt_pk_bf16_f32 v137, v138, v139
	v_pk_mul_f32 v[138:139], v[38:39], v[140:141] op_sel_hi:[1,0]
	v_pk_mul_f32 v[140:141], v[40:41], v[140:141] op_sel_hi:[1,0]
	v_exp_f32_e32 v138, v138
	v_exp_f32_e32 v139, v139
	v_exp_f32_e32 v140, v140
	v_exp_f32_e32 v141, v141
	v_pk_mul_f32 v[144:145], v[40:41], v[36:37]
	v_pk_add_f32 v[138:139], v[138:139], 1.0 op_sel_hi:[1,0]
	v_pk_mul_f32 v[142:143], v[144:145], v[142:143] op_sel_hi:[1,0]
	v_pk_add_f32 v[140:141], v[140:141], 1.0 op_sel_hi:[1,0]
	v_rcp_f32_e32 v138, v138
	v_rcp_f32_e32 v139, v139
	v_rcp_f32_e32 v140, v140
	v_rcp_f32_e32 v141, v141
	v_pk_mul_f32 v[138:139], v[146:147], v[138:139]
	s_nop 0
	v_cvt_pk_bf16_f32 v138, v138, v139
	v_pk_mul_f32 v[140:141], v[142:143], v[140:141]
	s_nop 0
	v_cvt_pk_bf16_f32 v139, v140, v141
	v_add_u32_e32 v140, 0x90, v195
	v_mad_i64_i32 v[140:141], s[0:1], v140, s80, v[132:133]
	v_lshl_add_u64 v[140:141], v[140:141], 0, v[134:135]
	flat_store_dwordx4 v[140:141], v[136:139] sc1
	v_mul_f32_e32 v140, 0xbfb8aa3b, v130
	v_mul_f32_e32 v130, v130, v130
	v_pk_mul_f32 v[136:137], v[30:31], v[140:141] op_sel_hi:[1,0]
	v_pk_mul_f32 v[142:143], v[26:27], v[130:131] op_sel_hi:[1,0]
	v_exp_f32_e32 v136, v136
	v_exp_f32_e32 v137, v137
	v_pk_mul_f32 v[138:139], v[32:33], v[28:29]
	v_pk_mul_f32 v[144:145], v[18:19], v[130:131] op_sel_hi:[1,0]
	v_pk_mul_f32 v[138:139], v[138:139], v[130:131] op_sel_hi:[1,0]
	v_pk_add_f32 v[136:137], v[136:137], 1.0 op_sel_hi:[1,0]
	s_nop 0
	v_rcp_f32_e32 v136, v136
	v_rcp_f32_e32 v137, v137
	s_nop 0
	v_pk_mul_f32 v[136:137], v[142:143], v[136:137]
	v_pk_mul_f32 v[142:143], v[32:33], v[140:141] op_sel_hi:[1,0]
	v_cvt_pk_bf16_f32 v136, v136, v137
	s_nop 0
	v_exp_f32_e32 v142, v142
	v_exp_f32_e32 v143, v143
	s_nop 0
	v_pk_add_f32 v[142:143], v[142:143], 1.0 op_sel_hi:[1,0]
	s_nop 0
	v_rcp_f32_e32 v142, v142
	v_rcp_f32_e32 v143, v143
	s_nop 0
	v_pk_mul_f32 v[138:139], v[138:139], v[142:143]
	s_nop 0
	v_cvt_pk_bf16_f32 v137, v138, v139
	v_pk_mul_f32 v[138:139], v[22:23], v[140:141] op_sel_hi:[1,0]
	v_pk_mul_f32 v[140:141], v[24:25], v[140:141] op_sel_hi:[1,0]
	v_exp_f32_e32 v138, v138
	v_exp_f32_e32 v139, v139
	v_exp_f32_e32 v140, v140
	v_exp_f32_e32 v141, v141
	v_pk_mul_f32 v[142:143], v[24:25], v[20:21]
	v_pk_add_f32 v[138:139], v[138:139], 1.0 op_sel_hi:[1,0]
	v_pk_mul_f32 v[142:143], v[142:143], v[130:131] op_sel_hi:[1,0]
	v_pk_add_f32 v[140:141], v[140:141], 1.0 op_sel_hi:[1,0]
	v_rcp_f32_e32 v138, v138
	v_rcp_f32_e32 v139, v139
	v_rcp_f32_e32 v140, v140
	v_rcp_f32_e32 v141, v141
	v_add_u32_e32 v130, 0xa0, v195
	v_pk_mul_f32 v[138:139], v[144:145], v[138:139]
	v_pk_mul_f32 v[144:145], v[6:7], v[2:3]
	v_pk_mul_f32 v[140:141], v[142:143], v[140:141]
	v_cvt_pk_bf16_f32 v138, v138, v139
	v_pk_mul_f32 v[142:143], v[14:15], v[10:11]
	v_cvt_pk_bf16_f32 v139, v140, v141
	v_mad_i64_i32 v[140:141], s[0:1], v130, s80, v[132:133]
	v_lshl_add_u64 v[140:141], v[140:141], 0, v[134:135]
	v_mul_f32_e32 v130, 0xbfb8aa3b, v131
	flat_store_dwordx4 v[140:141], v[136:139] sc1
	v_mul_f32_e32 v140, v131, v131
	v_pk_mul_f32 v[142:143], v[142:143], v[140:141] op_sel_hi:[1,0]
	v_pk_mul_f32 v[136:137], v[14:15], v[130:131] op_sel_hi:[1,0]
	v_pk_mul_f32 v[138:139], v[16:17], v[12:13]
	v_exp_f32_e32 v136, v136
	v_exp_f32_e32 v137, v137
	v_pk_mul_f32 v[138:139], v[138:139], v[140:141] op_sel_hi:[1,0]
	v_pk_mul_f32 v[144:145], v[144:145], v[140:141] op_sel_hi:[1,0]
	v_pk_add_f32 v[136:137], v[136:137], 1.0 op_sel_hi:[1,0]
	s_nop 0
	v_rcp_f32_e32 v136, v136
	v_rcp_f32_e32 v137, v137
	s_nop 0
	v_pk_mul_f32 v[136:137], v[142:143], v[136:137]
	v_pk_mul_f32 v[142:143], v[16:17], v[130:131] op_sel_hi:[1,0]
	v_cvt_pk_bf16_f32 v136, v136, v137
	s_nop 0
	v_exp_f32_e32 v142, v142
	v_exp_f32_e32 v143, v143
	s_nop 0
	v_pk_add_f32 v[142:143], v[142:143], 1.0 op_sel_hi:[1,0]
	s_nop 0
	v_rcp_f32_e32 v142, v142
	v_rcp_f32_e32 v143, v143
	s_nop 0
	v_pk_mul_f32 v[138:139], v[138:139], v[142:143]
	s_nop 0
	v_cvt_pk_bf16_f32 v137, v138, v139
	v_pk_mul_f32 v[138:139], v[6:7], v[130:131] op_sel_hi:[1,0]
	v_pk_mul_f32 v[130:131], v[8:9], v[130:131] op_sel_hi:[1,0]
	v_exp_f32_e32 v138, v138
	v_exp_f32_e32 v139, v139
	v_exp_f32_e32 v130, v130
	v_exp_f32_e32 v131, v131
	v_pk_mul_f32 v[142:143], v[8:9], v[4:5]
	v_pk_add_f32 v[138:139], v[138:139], 1.0 op_sel_hi:[1,0]
	v_pk_mul_f32 v[140:141], v[142:143], v[140:141] op_sel_hi:[1,0]
	v_pk_add_f32 v[130:131], v[130:131], 1.0 op_sel_hi:[1,0]
	v_rcp_f32_e32 v138, v138
	v_rcp_f32_e32 v139, v139
	v_rcp_f32_e32 v130, v130
	v_rcp_f32_e32 v131, v131
	v_pk_mul_f32 v[138:139], v[144:145], v[138:139]
	s_nop 0
	v_cvt_pk_bf16_f32 v138, v138, v139
	v_pk_mul_f32 v[130:131], v[140:141], v[130:131]
	s_nop 0
	v_cvt_pk_bf16_f32 v139, v130, v131
	v_add_u32_e32 v130, 0xb0, v195
	v_mad_i64_i32 v[130:131], s[0:1], v130, s80, v[132:133]
	v_lshl_add_u64 v[130:131], v[130:131], 0, v[134:135]
	flat_store_dwordx4 v[130:131], v[136:139] sc1
	s_cbranch_execz .LBB0_777
